# diff PV tail reordered (per-group exp/sum/pack interleaved with PV MFMAs, fewer waits/nops) on top of DMA + z changes
# speedup vs baseline: 1.0358x; 1.0200x over previous
.LBB0_260:
	s_or_b64 exec, exec, s[22:23]
	v_cmp_neq_f32_e32 vcc, v227, v226
	ds_read_b64_tr_b16 v[80:81], v0 offset:20480
	ds_read_b64_tr_b16 v[82:83], v14 offset:22528
	ds_read_b64_tr_b16 v[84:85], v15 offset:20480
	ds_read_b64_tr_b16 v[86:87], v221 offset:22528
	ds_read_b64_tr_b16 v[88:89], v222 offset:20480
	ds_read_b64_tr_b16 v[90:91], v223 offset:22528
	ds_read_b64_tr_b16 v[92:93], v224 offset:20480
	ds_read_b64_tr_b16 v[94:95], v225 offset:22528
	v_exp_f32_e32 v104, v112
	v_exp_f32_e32 v105, v113
	v_exp_f32_e32 v106, v114
	v_exp_f32_e32 v107, v115
	v_exp_f32_e32 v108, v116
	v_exp_f32_e32 v109, v117
	v_exp_f32_e32 v110, v118
	v_exp_f32_e32 v111, v119
	s_cbranch_vccz .Ldf_norescale
	v_sub_f32_e32 v246, v226, v227
	v_exp_f32_e32 v246, v246
	s_nop 0
	v_mul_f32_e32 v219, v219, v246
	v_pk_mul_f32 v[78:79], v[78:79], v[246:247] op_sel_hi:[1,0]
	v_pk_mul_f32 v[76:77], v[76:77], v[246:247] op_sel_hi:[1,0]
	v_pk_mul_f32 v[74:75], v[74:75], v[246:247] op_sel_hi:[1,0]
	v_pk_mul_f32 v[72:73], v[72:73], v[246:247] op_sel_hi:[1,0]
	v_pk_mul_f32 v[70:71], v[70:71], v[246:247] op_sel_hi:[1,0]
	v_pk_mul_f32 v[68:69], v[68:69], v[246:247] op_sel_hi:[1,0]
	v_pk_mul_f32 v[66:67], v[66:67], v[246:247] op_sel_hi:[1,0]
	v_pk_mul_f32 v[64:65], v[64:65], v[246:247] op_sel_hi:[1,0]
	v_pk_mul_f32 v[62:63], v[62:63], v[246:247] op_sel_hi:[1,0]
	v_pk_mul_f32 v[60:61], v[60:61], v[246:247] op_sel_hi:[1,0]
	v_pk_mul_f32 v[58:59], v[58:59], v[246:247] op_sel_hi:[1,0]
	v_pk_mul_f32 v[56:57], v[56:57], v[246:247] op_sel_hi:[1,0]
	v_pk_mul_f32 v[54:55], v[54:55], v[246:247] op_sel_hi:[1,0]
	v_pk_mul_f32 v[52:53], v[52:53], v[246:247] op_sel_hi:[1,0]
	v_pk_mul_f32 v[50:51], v[50:51], v[246:247] op_sel_hi:[1,0]
	v_pk_mul_f32 v[48:49], v[48:49], v[246:247] op_sel_hi:[1,0]
	v_pk_mul_f32 v[46:47], v[46:47], v[246:247] op_sel_hi:[1,0]
	v_pk_mul_f32 v[44:45], v[44:45], v[246:247] op_sel_hi:[1,0]
	v_pk_mul_f32 v[42:43], v[42:43], v[246:247] op_sel_hi:[1,0]
	v_pk_mul_f32 v[40:41], v[40:41], v[246:247] op_sel_hi:[1,0]
	v_pk_mul_f32 v[38:39], v[38:39], v[246:247] op_sel_hi:[1,0]
	v_pk_mul_f32 v[36:37], v[36:37], v[246:247] op_sel_hi:[1,0]
	v_pk_mul_f32 v[34:35], v[34:35], v[246:247] op_sel_hi:[1,0]
	v_pk_mul_f32 v[32:33], v[32:33], v[246:247] op_sel_hi:[1,0]
	v_pk_mul_f32 v[30:31], v[30:31], v[246:247] op_sel_hi:[1,0]
	v_pk_mul_f32 v[28:29], v[28:29], v[246:247] op_sel_hi:[1,0]
	v_pk_mul_f32 v[26:27], v[26:27], v[246:247] op_sel_hi:[1,0]
	v_pk_mul_f32 v[24:25], v[24:25], v[246:247] op_sel_hi:[1,0]
	v_pk_mul_f32 v[22:23], v[22:23], v[246:247] op_sel_hi:[1,0]
	v_pk_mul_f32 v[20:21], v[20:21], v[246:247] op_sel_hi:[1,0]
	v_pk_mul_f32 v[18:19], v[18:19], v[246:247] op_sel_hi:[1,0]
	v_pk_mul_f32 v[16:17], v[16:17], v[246:247] op_sel_hi:[1,0]
.Ldf_norescale:
	v_add_f32_e32 v238, v104, v105
	v_add_f32_e32 v239, v106, v107
	v_add_f32_e32 v240, v108, v109
	v_add_f32_e32 v241, v110, v111
	v_add_f32_e32 v238, v238, v239
	v_add_f32_e32 v240, v240, v241
	v_cvt_pk_bf16_f32 v104, v104, v105
	v_cvt_pk_bf16_f32 v105, v106, v107
	v_cvt_pk_bf16_f32 v106, v108, v109
	v_cvt_pk_bf16_f32 v107, v110, v111
	v_add_f32_e32 v238, v238, v240
	v_add_f32_e32 v219, v219, v238
	s_waitcnt lgkmcnt(8)
	v_mfma_f32_32x32x16_bf16 v[64:79], v[2:5], v[104:107], v[64:79]
	v_exp_f32_e32 v96, v120
	v_exp_f32_e32 v97, v121
	v_exp_f32_e32 v98, v122
	v_exp_f32_e32 v99, v123
	v_mfma_f32_32x32x16_bf16 v[48:63], v[6:9], v[104:107], v[48:63]
	v_exp_f32_e32 v100, v124
	v_exp_f32_e32 v101, v125
	v_exp_f32_e32 v102, v126
	v_exp_f32_e32 v103, v127
	v_mfma_f32_32x32x16_bf16 v[32:47], v[10:13], v[104:107], v[32:47]
	v_add_f32_e32 v238, v96, v97
	v_add_f32_e32 v239, v98, v99
	v_add_f32_e32 v240, v100, v101
	v_add_f32_e32 v241, v102, v103
	v_add_f32_e32 v238, v238, v239
	v_add_f32_e32 v240, v240, v241
	v_mfma_f32_32x32x16_bf16 v[16:31], v[160:163], v[104:107], v[16:31]
	ds_read_b64_tr_b16 v[2:3], v0 offset:24576
	ds_read_b64_tr_b16 v[4:5], v14 offset:26624
	ds_read_b64_tr_b16 v[6:7], v15 offset:24576
	ds_read_b64_tr_b16 v[8:9], v221 offset:26624
	ds_read_b64_tr_b16 v[10:11], v222 offset:24576
	ds_read_b64_tr_b16 v[12:13], v223 offset:26624
	ds_read_b64_tr_b16 v[160:161], v224 offset:24576
	ds_read_b64_tr_b16 v[162:163], v225 offset:26624
	v_cvt_pk_bf16_f32 v96, v96, v97
	v_cvt_pk_bf16_f32 v97, v98, v99
	v_cvt_pk_bf16_f32 v98, v100, v101
	v_cvt_pk_bf16_f32 v99, v102, v103
	v_add_f32_e32 v238, v238, v240
	v_add_f32_e32 v219, v219, v238
	s_waitcnt lgkmcnt(8)
	v_mfma_f32_32x32x16_bf16 v[64:79], v[80:83], v[96:99], v[64:79]
	v_exp_f32_e32 v112, v128
	v_exp_f32_e32 v113, v129
	v_exp_f32_e32 v114, v130
	v_exp_f32_e32 v115, v131
	v_mfma_f32_32x32x16_bf16 v[48:63], v[84:87], v[96:99], v[48:63]
	v_exp_f32_e32 v116, v132
	v_exp_f32_e32 v117, v133
	v_exp_f32_e32 v118, v134
	v_exp_f32_e32 v119, v135
	v_mfma_f32_32x32x16_bf16 v[32:47], v[88:91], v[96:99], v[32:47]
	v_add_f32_e32 v238, v112, v113
	v_add_f32_e32 v239, v114, v115
	v_add_f32_e32 v240, v116, v117
	v_add_f32_e32 v241, v118, v119
	v_add_f32_e32 v238, v238, v239
	v_add_f32_e32 v240, v240, v241
	v_mfma_f32_32x32x16_bf16 v[16:31], v[92:95], v[96:99], v[16:31]
	ds_read_b64_tr_b16 v[80:81], v0 offset:28672
	ds_read_b64_tr_b16 v[82:83], v14 offset:30720
	ds_read_b64_tr_b16 v[84:85], v15 offset:28672
	ds_read_b64_tr_b16 v[86:87], v221 offset:30720
	ds_read_b64_tr_b16 v[88:89], v222 offset:28672
	ds_read_b64_tr_b16 v[90:91], v223 offset:30720
	ds_read_b64_tr_b16 v[92:93], v224 offset:28672
	ds_read_b64_tr_b16 v[94:95], v225 offset:30720
	v_cvt_pk_bf16_f32 v112, v112, v113
	v_cvt_pk_bf16_f32 v113, v114, v115
	v_cvt_pk_bf16_f32 v114, v116, v117
	v_cvt_pk_bf16_f32 v115, v118, v119
	v_add_f32_e32 v238, v238, v240
	v_add_f32_e32 v219, v219, v238
	s_waitcnt lgkmcnt(8)
	v_mfma_f32_32x32x16_bf16 v[64:79], v[2:5], v[112:115], v[64:79]
	v_exp_f32_e32 v120, v136
	v_exp_f32_e32 v121, v137
	v_exp_f32_e32 v122, v138
	v_exp_f32_e32 v123, v139
	v_mfma_f32_32x32x16_bf16 v[48:63], v[6:9], v[112:115], v[48:63]
	v_exp_f32_e32 v124, v140
	v_exp_f32_e32 v125, v141
	v_exp_f32_e32 v126, v142
	v_exp_f32_e32 v127, v143
	v_mfma_f32_32x32x16_bf16 v[32:47], v[10:13], v[112:115], v[32:47]
	v_add_f32_e32 v238, v120, v121
	v_add_f32_e32 v239, v122, v123
	v_add_f32_e32 v240, v124, v125
	v_add_f32_e32 v241, v126, v127
	v_add_f32_e32 v238, v238, v239
	v_add_f32_e32 v240, v240, v241
	v_mfma_f32_32x32x16_bf16 v[16:31], v[160:163], v[112:115], v[16:31]
	v_cvt_pk_bf16_f32 v120, v120, v121
	v_cvt_pk_bf16_f32 v121, v122, v123
	v_cvt_pk_bf16_f32 v122, v124, v125
	v_cvt_pk_bf16_f32 v123, v126, v127
	v_add_f32_e32 v238, v238, v240
	v_add_f32_e32 v219, v219, v238
	s_waitcnt lgkmcnt(6)
	v_mfma_f32_32x32x16_bf16 v[64:79], v[80:83], v[120:123], v[64:79]
	s_waitcnt lgkmcnt(4)
	v_mfma_f32_32x32x16_bf16 v[48:63], v[84:87], v[120:123], v[48:63]
	s_waitcnt lgkmcnt(2)
	v_mfma_f32_32x32x16_bf16 v[32:47], v[88:91], v[120:123], v[32:47]
	s_waitcnt lgkmcnt(0)
	v_mfma_f32_32x32x16_bf16 v[16:31], v[92:95], v[120:123], v[16:31]
